# mLSTM: LDS-DMA staging issued after barrier 2 (Qs fragment reads for [C] hoisted above it)
# speedup vs baseline: 1.0239x; 1.0239x over previous
.LBB0_659:
	s_or_b64 exec, exec, s[4:5]
	s_lshr_b32 s4, s92, 3
	s_and_b32 s59, s4, 3
	s_lshl_b32 s97, s94, 6
	s_cmp_gt_i32 s55, 3
	s_cselect_b64 s[68:69], -1, 0
	s_add_i32 s4, s55, -4
	s_lshr_b32 s6, s4, 1
	v_and_b32_e32 v99, 48, v83
	v_bfe_u32 v222, v83, 5, 1
	v_lshlrev_b32_e32 v222, 4, v222
	v_bfe_u32 v223, v83, 4, 1
	v_lshl_or_b32 v222, v223, 8, v222
	v_bfe_u32 v223, v83, 5, 1
	v_mul_u32_u24_e32 v223, 0xf0, v223
	v_lshrrev_b32_e32 v226, 1, v83
	v_and_b32_e32 v226, 0xffffffe0, v226
	v_sub_u32_e32 v223, v223, v226
	v_bfe_u32 v224, v83, 2, 3
	v_lshlrev_b32_e32 v224, 5, v224
	v_bfe_u32 v227, v83, 1, 1
	v_lshl_or_b32 v224, v227, 4, v224
	v_and_b32_e32 v228, 1, v83
	v_lshl_or_b32 v224, v228, 8, v224
	v_lshlrev_b32_e32 v225, 8, v227
	v_lshl_or_b32 v225, v228, 3, v225
	v_add_u32_e32 v225, v225, v226
	s_lshl_b32 s4, s55, 4
	v_lshl_add_u32 v103, s6, 7, v222
	s_lshl_b32 s6, s6, 5
	v_lshlrev_b32_e32 v66, 2, v84
	s_and_b32 s17, s4, 16
	s_add_i32 s6, s6, 64
	s_ashr_i32 s70, s12, 7
	s_bfe_u32 s71, s12, 0x10006
	v_lshl_add_u32 v21, v24, 4, 0
	v_add_u32_e32 v106, 0, v66
	v_or_b32_e32 v88, s17, v84
	v_mul_u32_u24_e32 v24, 0x20c, v84
	s_mov_b32 s4, 0xc000
	s_cmp_lg_u32 s70, 1
	v_add3_u32 v105, v106, v24, s4
	v_or_b32_e32 v24, s6, v88
	s_cselect_b64 s[6:7], -1, 0
	s_bitcmp1_b32 s12, 6
	s_cselect_b64 s[8:9], -1, 0
	s_or_b64 s[64:65], s[6:7], s[8:9]
	s_lshl_b32 s6, s70, 4
	v_lshlrev_b32_e32 v102, 2, v24
	v_or_b32_e32 v24, s6, v84
	v_mul_lo_u32 v24, v24, s83
	v_lshlrev_b32_e32 v68, 2, v23
	v_add_u32_e32 v101, 0, v24
	v_or_b32_e32 v98, s6, v68
	s_and_b32 s6, s12, 0xffffff80
	v_lshrrev_b32_e32 v24, 2, v84
	s_add_i32 s86, s35, s6
	v_or_b32_e32 v24, v26, v24
	s_ashr_i32 s6, s12, 3
	s_lshl_b32 s16, s58, 9
	v_mad_u32_u24 v28, v24, s83, 0
	v_lshlrev_b32_e32 v24, 3, v83
	s_and_b32 s56, s6, -16
	s_add_i32 s42, s42, s16
	v_and_or_b32 v29, v24, 24, s13
	v_or_b32_e32 v24, s56, v84
	s_and_b32 s16, s42, 0xfffff800
	v_mul_lo_u32 v26, v24, s82
	s_or_b32 s17, s16, s17
	v_add_u32_e32 v70, 0, v26
	s_movk_i32 s6, 0x1c0
	v_or_b32_e32 v109, s17, v84
	s_lshl_b32 s17, s70, 6
	v_cmp_gt_u32_e64 s[4:5], 16, v27
	v_lshl_or_b32 v96, s71, 4, v84
	v_mad_u64_u32 v[26:27], s[6:7], v24, s6, v[70:71]
	v_or_b32_e32 v24, 2, v98
	s_add_i32 s17, s17, 0x18500
	v_cmp_gt_i32_e64 s[10:11], v24, v96
	v_or_b32_e32 v24, 3, v98
	v_lshl_or_b32 v111, v23, 4, s17
	v_mul_hi_u32_u24_e32 v23, 0x7000, v84
	s_mul_hi_i32 s42, s16, 0x3800
	v_mul_lo_u32 v108, v25, s87
	v_cmp_gt_i32_e64 s[6:7], v24, v96
	v_mul_u32_u24_e32 v24, 0x7000, v84
	s_mul_i32 s58, s16, 0x3800
	v_or_b32_e32 v25, s42, v23
	s_lshl_b32 s42, s92, 4
	v_or_b32_e32 v23, s58, v24
	s_and_b32 s42, s42, 0x600
	s_mul_i32 s100, s16, 0x3800
	s_mul_hi_u32 s101, s16, 0x3800
	s_add_u32 s100, s100, s28
	s_addc_u32 s101, s101, s29
	s_add_u32 s100, s100, s42
	s_addc_u32 s101, s101, 0
	s_add_u32 s100, s100, 0x2000
	s_addc_u32 s101, s101, 0
	v_or_b32_e32 v23, s42, v23
	s_ashr_i32 s17, s16, 31
	v_lshl_or_b32 v24, s59, 7, v23
	v_mul_lo_u32 v27, v16, s83
	v_lshl_add_u64 v[18:19], v[18:19], 1, v[24:25]
	v_lshl_add_u64 v[16:17], v[16:17], 0, s[16:17]
	s_waitcnt lgkmcnt(0)
	s_barrier
; #define LAS __attribute__((address_space(3)))
; __device__ __forceinline__ void mlstm_item(const Args& a, LAS unsigned char* L, bool sample, int b, int hh, int sl, bool dry = false) {
;     ...
;             for (int kk = 0; kk < 8; ++kk) { Af[kk] = *(const LAS bf16x8*)(L + L_CS + (vt * 16 + lr) * 528 + kk * 64 + g * 16); Bf[kk] = *(const LAS bf16x8*)(L + L_QS + t * 528 + kk * 64 + g * 16); }
	v_mad_u32_u24 v104, v88, s83, 0
	v_lshl_add_u64 v[72:73], s[28:29], 0, v[18:19]
	v_mad_u64_u32 v[18:19], s[16:17], v16, s84, 0
	v_mul_u32_u24_e32 v20, 0x210, v84
	v_lshlrev_b32_e32 v107, 3, v84
	v_mad_u32_u24 v100, v96, s83, 0
	v_add_u32_e32 v30, 0, v99
	v_mad_i32_i24 v31, v88, s33, v104
	v_mul_u32_u24_e32 v32, 0x50, v84
	v_mad_i32_i24 v17, v17, s84, v19
	v_or3_b32 v16, v18, s42, v60
	v_mov_b32_e32 v36, 0
	v_cmp_gt_i32_e64 s[14:15], 16, v83
	v_mad_i32_i24 v93, v96, s33, v100
	v_lshlrev_b32_e32 v94, 1, v98
	v_lshlrev_b32_e32 v92, 2, v96
	v_lshl_add_u32 v89, v88, 2, s35
	s_ashr_i32 s57, s56, 31
	v_cmp_gt_i32_e64 s[12:13], v98, v96
	v_cmp_lt_i32_e64 s[8:9], v98, v96
	v_lshl_or_b32 v110, s71, 6, v66
	v_lshl_add_u64 v[74:75], s[28:29], 0, v[16:17]
	s_mov_b32 s16, 0
	s_mov_b64 s[70:71], 0
	s_lshl_b32 s58, s97, 1
	v_lshlrev_b32_e32 v60, 1, v68
	v_add_u32_e32 v112, v224, v27
	v_add_u32_e32 v97, v28, v225
	v_add_u32_e32 v95, v30, v32
	v_add_u32_e32 v91, v31, v99
	v_add_u32_e32 v90, v26, v222
	v_add_u32_e32 v113, v22, v20
	v_add_u32_e32 v113, v113, v223
	v_add_u32_e32 v86, v86, v223
	v_add_u32_e32 v85, v85, v223
	v_add_u32_e32 v67, v67, v223
	v_mov_b32_e32 v114, v107
	v_mov_b32_e32 v37, v36
	v_mov_b32_e32 v38, v36
	v_mov_b32_e32 v39, v36
	v_mov_b32_e32 v52, v36
	v_mov_b32_e32 v53, v36
	v_mov_b32_e32 v54, v36
	v_mov_b32_e32 v55, v36
	v_mov_b32_e32 v48, v36
	v_mov_b32_e32 v49, v36
	v_mov_b32_e32 v50, v36
	v_mov_b32_e32 v51, v36
	v_mov_b32_e32 v44, v36
	v_mov_b32_e32 v45, v36
	v_mov_b32_e32 v46, v36
	v_mov_b32_e32 v47, v36
	v_mov_b32_e32 v40, v36
	v_mov_b32_e32 v41, v36
	v_mov_b32_e32 v42, v36
	v_mov_b32_e32 v43, v36
	v_mov_b32_e32 v32, v36
	v_mov_b32_e32 v33, v36
	v_mov_b32_e32 v34, v36
	v_mov_b32_e32 v35, v36
	v_mov_b32_e32 v28, v36
	v_mov_b32_e32 v29, v36
	v_mov_b32_e32 v30, v36
	v_mov_b32_e32 v31, v36
	v_mov_b32_e32 v24, v36
	v_mov_b32_e32 v25, v36
	v_mov_b32_e32 v26, v36
	v_mov_b32_e32 v27, v36
	v_mov_b32_e32 v20, v36
	v_mov_b32_e32 v21, v36
	v_mov_b32_e32 v22, v36
	v_mov_b32_e32 v23, v36
	v_mov_b32_e32 v16, v36
	v_mov_b32_e32 v17, v36
	v_mov_b32_e32 v18, v36
	v_mov_b32_e32 v19, v36
	v_add_u32_e32 v239, v104, v222
	v_mov_b32_e32 v234, v83
	v_mul_u32_u24_e32 v235, 0x7c2, v234
	v_lshrrev_b32_e32 v235, 16, v235
	v_mul_u32_u24_e32 v236, 33, v235
	v_sub_u32_e32 v236, v234, v236
	v_and_b32_e32 v237, 15, v236
	v_lshrrev_b32_e32 v238, 1, v237
	v_lshlrev_b32_e32 v238, 6, v238
	v_and_b32_e32 v237, 1, v237
	v_lshl_or_b32 v238, v237, 5, v238
	v_lshrrev_b32_e32 v237, 4, v236
	v_lshl_or_b32 v238, v237, 4, v238
	v_lshrrev_b32_e32 v237, 5, v235
	v_lshl_or_b32 v238, v237, 11, v238
	v_and_b32_e32 v237, 31, v235
	v_mul_u32_u24_e32 v237, 0x3800, v237
	v_add_u32_e32 v229, v237, v238
	v_add_u32_e32 v234, 512, v83
	v_mul_u32_u24_e32 v235, 0x7c2, v234
	v_lshrrev_b32_e32 v235, 16, v235
	v_mul_u32_u24_e32 v236, 33, v235
	v_sub_u32_e32 v236, v234, v236
	v_and_b32_e32 v237, 15, v236
	v_lshrrev_b32_e32 v238, 1, v237
	v_lshlrev_b32_e32 v238, 6, v238
	v_and_b32_e32 v237, 1, v237
	v_lshl_or_b32 v238, v237, 5, v238
	v_lshrrev_b32_e32 v237, 4, v236
	v_lshl_or_b32 v238, v237, 4, v238
	v_lshrrev_b32_e32 v237, 5, v235
	v_lshl_or_b32 v238, v237, 11, v238
	v_and_b32_e32 v237, 31, v235
	v_mul_u32_u24_e32 v237, 0x3800, v237
	v_add_u32_e32 v230, v237, v238
	v_add_u32_e32 v234, 1024, v83
	v_mul_u32_u24_e32 v235, 0x7c2, v234
	v_lshrrev_b32_e32 v235, 16, v235
	v_mul_u32_u24_e32 v236, 33, v235
	v_sub_u32_e32 v236, v234, v236
	v_and_b32_e32 v237, 15, v236
	v_lshrrev_b32_e32 v238, 1, v237
	v_lshlrev_b32_e32 v238, 6, v238
	v_and_b32_e32 v237, 1, v237
	v_lshl_or_b32 v238, v237, 5, v238
	v_lshrrev_b32_e32 v237, 4, v236
	v_lshl_or_b32 v238, v237, 4, v238
	v_lshrrev_b32_e32 v237, 5, v235
	v_lshl_or_b32 v238, v237, 11, v238
	v_and_b32_e32 v237, 31, v235
	v_mul_u32_u24_e32 v237, 0x3800, v237
	v_add_u32_e32 v231, v237, v238
	v_add_u32_e32 v234, 1536, v83
	v_mul_u32_u24_e32 v235, 0x7c2, v234
	v_lshrrev_b32_e32 v235, 16, v235
	v_mul_u32_u24_e32 v236, 33, v235
	v_sub_u32_e32 v236, v234, v236
	v_and_b32_e32 v237, 15, v236
	v_lshrrev_b32_e32 v238, 1, v237
	v_lshlrev_b32_e32 v238, 6, v238
	v_and_b32_e32 v237, 1, v237
	v_lshl_or_b32 v238, v237, 5, v238
	v_lshrrev_b32_e32 v237, 4, v236
	v_lshl_or_b32 v238, v237, 4, v238
	v_lshrrev_b32_e32 v237, 5, v235
	v_lshl_or_b32 v238, v237, 11, v238
	v_and_b32_e32 v237, 31, v235
	v_mul_u32_u24_e32 v237, 0x3800, v237
	v_add_u32_e32 v232, v237, v238
	v_add_u32_e32 v234, 2048, v83
	v_mul_u32_u24_e32 v235, 0x7c2, v234
	v_lshrrev_b32_e32 v235, 16, v235
	v_mul_u32_u24_e32 v236, 33, v235
	v_sub_u32_e32 v236, v234, v236
	v_and_b32_e32 v237, 15, v236
	v_lshrrev_b32_e32 v238, 1, v237
	v_lshlrev_b32_e32 v238, 6, v238
	v_and_b32_e32 v237, 1, v237
	v_lshl_or_b32 v238, v237, 5, v238
	v_lshrrev_b32_e32 v237, 4, v236
	v_lshl_or_b32 v238, v237, 4, v238
	v_lshrrev_b32_e32 v237, 5, v235
	v_lshl_or_b32 v238, v237, 11, v238
	v_and_b32_e32 v237, 31, v235
	v_mul_u32_u24_e32 v237, 0x3800, v237
	v_add_u32_e32 v233, v237, v238
	s_add_u32 s98, s100, s70
	s_addc_u32 s99, s101, s71
	s_lshl_b32 m0, s55, 10
	s_nop 0
	global_load_lds_dwordx4 v229, s[98:99]
	s_add_u32 m0, m0, 0x2000
	s_nop 0
	global_load_lds_dwordx4 v230, s[98:99]
	s_add_u32 m0, m0, 0x2000
	s_nop 0
	global_load_lds_dwordx4 v231, s[98:99]
	s_add_u32 m0, m0, 0x2000
	s_nop 0
	global_load_lds_dwordx4 v232, s[98:99]
	s_cmp_lg_u32 s55, 0
	s_cbranch_scc1 .Ldma_skip_pro
	s_mov_b32 m0, 0x8000
	s_nop 0
	global_load_lds_dwordx4 v233, s[98:99]

; #define LAS __attribute__((address_space(3)))
; #define MFMA16(a, b, c) __builtin_amdgcn_mfma_f32_16x16x32_bf16((a), (b), (c), 0, 0, 0)
; #define LDS_BARRIER() do { asm volatile("s_waitcnt lgkmcnt(0)" ::: "memory"); __builtin_amdgcn_s_barrier(); asm volatile("" ::: "memory"); } while (0)
; __device__ __forceinline__ void mlstm_item(const Args& a, LAS unsigned char* L, bool sample, int b, int hh, int sl, bool dry = false) {
;     ...
;         {
;             typedef short v4i16_t __attribute__((ext_vector_type(4)));
;             v4i16_t tl[2], th[2]; bf16x8 Bv[5];
; #pragma unroll
;             for (int kti = 0; kti < 2; ++kti) { const int kt = 2 * wave + kti;
;                 tl[kti] = __builtin_amdgcn_ds_read_tr16_b64_v4i16((LAS v4i16_t*)(L + L_KS + (g * 8 + (lr >> 2)) * 528 + (kt * 16 + 4 * (lr & 3)) * 2));
;                 th[kti] = __builtin_amdgcn_ds_read_tr16_b64_v4i16((LAS v4i16_t*)(L + L_KS + (g * 8 + 4 + (lr >> 2)) * 528 + (kt * 16 + 4 * (lr & 3)) * 2)); }
; #pragma unroll
;             for (int vt = 0; vt < 5; ++vt) Bv[vt] = *(const LAS bf16x8*)(L + L_VTW + (vt * 16 + lr) * 80 + g * 16);
; #pragma unroll
;             for (int kti = 0; kti < 2; ++kti) { const bf16x8 A = (bf16x8){tl[kti][0], tl[kti][1], tl[kti][2], tl[kti][3], th[kti][0], th[kti][1], th[kti][2], th[kti][3]};
; #pragma unroll
;                 for (int vt = 0; vt < 5; ++vt) Cacc[kti][vt] = MFMA16(A, Bv[vt], Cacc[kti][vt] * dL); }
;         }
;         LDS_BARRIER();
;         {
;             const int tt = wave & 1, vt = wave >> 1, t = tt * 16 + lr;
;             const bf16x8 Bs = *(const LAS bf16x8*)(L + L_SS + t * 80 + g * 16);
;             const f32x4 z4 = (f32x4){0.f, 0.f, 0.f, 0.f};
;             const bf16x8 Av = *(const LAS bf16x8*)(L + L_VT + (vt * 16 + lr) * 80 + g * 16);
;             bf16x8 Af[8], Bf[8];
; #pragma unroll
;             for (int kk = 0; kk < 8; ++kk) { Af[kk] = *(const LAS bf16x8*)(L + L_CS + (vt * 16 + lr) * 528 + kk * 64 + g * 16); Bf[kk] = *(const LAS bf16x8*)(L + L_QS + t * 528 + kk * 64 + g * 16); }
.LBB0_661:
	ds_read_b64_tr_b16 v[58:59], v97 offset:19008
	s_waitcnt lgkmcnt(1)
	ds_read_b64_tr_b16 v[56:57], v97 offset:16896
	ds_read_b64_tr_b16 v[116:117], v97 offset:16912
	ds_read_b64_tr_b16 v[118:119], v97 offset:19024
	ds_read_b128 v[120:123], v95 offset:40192
	ds_read_b128 v[124:127], v95 offset:41472
	ds_read_b128 v[128:131], v95 offset:42752
	ds_read_b128 v[132:135], v95 offset:44032
	ds_read_b128 v[136:139], v95 offset:45312
	ds_read_b128 v[190:193], v239
	ds_read_b128 v[194:197], v239 offset:32
	ds_read_b128 v[198:201], v239 offset:64
	ds_read_b128 v[202:205], v239 offset:96
	ds_read_b128 v[206:209], v239 offset:128
	ds_read_b128 v[210:213], v239 offset:160
	ds_read_b128 v[214:217], v239 offset:192
	ds_read_b128 v[218:221], v239 offset:224
	v_pk_mul_f32 v[38:39], v[38:39], v[76:77] op_sel_hi:[1,0]
	v_pk_mul_f32 v[36:37], v[36:37], v[76:77] op_sel_hi:[1,0]
	v_pk_mul_f32 v[54:55], v[54:55], v[76:77] op_sel_hi:[1,0]
	v_pk_mul_f32 v[52:53], v[52:53], v[76:77] op_sel_hi:[1,0]
	v_pk_mul_f32 v[50:51], v[50:51], v[76:77] op_sel_hi:[1,0]
	v_pk_mul_f32 v[48:49], v[48:49], v[76:77] op_sel_hi:[1,0]
	v_pk_mul_f32 v[46:47], v[46:47], v[76:77] op_sel_hi:[1,0]
	v_pk_mul_f32 v[44:45], v[44:45], v[76:77] op_sel_hi:[1,0]
	v_pk_mul_f32 v[42:43], v[42:43], v[76:77] op_sel_hi:[1,0]
	v_pk_mul_f32 v[40:41], v[40:41], v[76:77] op_sel_hi:[1,0]
	s_waitcnt lgkmcnt(12)
	v_mfma_f32_16x16x32_bf16 v[36:39], v[56:59], v[120:123], v[36:39]
	v_mul_f32_e64 v34, v34, v76
	v_mul_f32_e64 v35, v35, v76
	v_pk_mul_f32 v[32:33], v[32:33], v[76:77] op_sel_hi:[1,0]
	v_pk_mul_f32 v[30:31], v[30:31], v[76:77] op_sel_hi:[1,0]
	s_waitcnt lgkmcnt(11)
	v_mfma_f32_16x16x32_bf16 v[52:55], v[56:59], v[124:127], v[52:55]
	v_mul_f32_e64 v28, v28, v76
	v_mul_f32_e64 v29, v29, v76
	v_pk_mul_f32 v[26:27], v[26:27], v[76:77] op_sel_hi:[1,0]
	v_pk_mul_f32 v[24:25], v[24:25], v[76:77] op_sel_hi:[1,0]
	s_waitcnt lgkmcnt(10)
	v_mfma_f32_16x16x32_bf16 v[48:51], v[56:59], v[128:131], v[48:51]
	v_mul_f32_e64 v22, v22, v76
	v_mul_f32_e64 v23, v23, v76
	v_pk_mul_f32 v[20:21], v[20:21], v[76:77] op_sel_hi:[1,0]
	v_pk_mul_f32 v[18:19], v[18:19], v[76:77] op_sel_hi:[1,0]
	s_waitcnt lgkmcnt(9)
	v_mfma_f32_16x16x32_bf16 v[44:47], v[56:59], v[132:135], v[44:47]
	v_mul_f32_e64 v16, v16, v76
	v_mul_f32_e64 v17, v17, v76
	s_waitcnt lgkmcnt(0)
	s_barrier
	s_add_u32 s98, s100, s70
	s_addc_u32 s99, s101, s71
	s_add_u32 s98, s98, 0x70000
	s_addc_u32 s99, s99, 0
	s_lshl_b32 m0, s55, 10
	s_nop 0
	global_load_lds_dwordx4 v229, s[98:99]
	s_add_u32 m0, m0, 0x2000
	s_nop 0
	global_load_lds_dwordx4 v230, s[98:99]
	s_add_u32 m0, m0, 0x2000
	s_nop 0
	global_load_lds_dwordx4 v231, s[98:99]
	s_add_u32 m0, m0, 0x2000
	s_nop 0
	global_load_lds_dwordx4 v232, s[98:99]
	s_cmp_lg_u32 s55, 0
	s_cbranch_scc1 .Ldma_skip_loop
	s_mov_b32 m0, 0x8000
	s_nop 0
	global_load_lds_dwordx4 v233, s[98:99]
; #define LAS __attribute__((address_space(3)))
; __device__ __forceinline__ unsigned pk2(float lo, float hi) { unsigned r; asm("v_cvt_pk_bf16_f32 %0, %1, %2" : "=v"(r) : "v"(lo), "v"(hi)); return r; }
; #define MFMA16(a, b, c) __builtin_amdgcn_mfma_f32_16x16x32_bf16((a), (b), (c), 0, 0, 0)
; #define LDS_BARRIER() do { asm volatile("s_waitcnt lgkmcnt(0)" ::: "memory"); __builtin_amdgcn_s_barrier(); asm volatile("" ::: "memory"); } while (0)
; __device__ __forceinline__ void mlstm_item(const Args& a, LAS unsigned char* L, bool sample, int b, int hh, int sl, bool dry = false) {
;     ...
;         {
;             const int tt = wave & 1, vt = wave >> 1, t = tt * 16 + lr;
;             const bf16x8 Bs = *(const LAS bf16x8*)(L + L_SS + t * 80 + g * 16);
;             const f32x4 z4 = (f32x4){0.f, 0.f, 0.f, 0.f};
;             const bf16x8 Av = *(const LAS bf16x8*)(L + L_VT + (vt * 16 + lr) * 80 + g * 16);
;             bf16x8 Af[8], Bf[8];
; #pragma unroll
;             for (int kk = 0; kk < 8; ++kk) { Af[kk] = *(const LAS bf16x8*)(L + L_CS + (vt * 16 + lr) * 528 + kk * 64 + g * 16); Bf[kk] = *(const LAS bf16x8*)(L + L_QS + t * 528 + kk * 64 + g * 16); }
;             __builtin_amdgcn_sched_barrier(0);
;             f32x4 sM = MFMA16(Av, Bs, z4);
;             f32x4 cM = z4;
; #pragma unroll
;             for (int kk = 0; kk < 8; ++kk) cM = MFMA16(Af[kk], Bf[kk], cM);
;             const float d0 = __expf(m0c + GFM[c * 32 + t]), en = GEN[c * 32 + t];
;             const LAS float* NQ = (const LAS float*)(L + L_NQ);
;             const float nq = (NQ[t] + NQ[32 + t]) + d0 * (NQ[64 + t] + NQ[96 + t]);
;             const float inv = __builtin_amdgcn_rcpf(fmaxf(fabsf(nq), en));
;             float hv[4];
; #pragma unroll
;             for (int j = 0; j < 4; ++j) hv[j] = (sM[j] + d0 * cM[j]) * inv;
;             if (dry) *(u32x2*)((bf16_t*)a.out + (size_t)(rowbase + c * 32 + t) * 1024 + hh * 256 + sl * 64 + vt * 16 + g * 4) = (u32x2){pk2(hv[0], hv[1]), pk2(hv[2], hv[3])};
;             else *(u32x2*)(U + (size_t)(rowbase + c * 32 + t) * LDU + C_V + hh * 256 + sl * 64 + vt * 16 + g * 4) = (u32x2){pk2(hv[0], hv[1]), pk2(hv[2], hv[3])};
;         }
;         LDS_BARRIER();
;         WRITE_CS();
.Ldma_skip_loop:
	s_waitcnt lgkmcnt(0)
	v_mfma_f32_16x16x32_bf16 v[40:43], v[56:59], v[136:139], v[40:43]
	v_add_u32_e32 v58, v70, v99
	v_add_u32_e32 v57, v104, v222
	v_mfma_f32_16x16x32_bf16 v[32:35], v[116:119], v[120:123], v[32:35]
	v_mfma_f32_16x16x32_bf16 v[28:31], v[116:119], v[124:127], v[28:31]
	v_mfma_f32_16x16x32_bf16 v[24:27], v[116:119], v[128:131], v[24:27]
	v_mfma_f32_16x16x32_bf16 v[20:23], v[116:119], v[132:135], v[20:23]
	v_mfma_f32_16x16x32_bf16 v[16:19], v[116:119], v[136:139], v[16:19]
	ds_read_b128 v[116:119], v91 offset:46592
	ds_read_b128 v[120:123], v58 offset:33792
	ds_read_b128 v[124:127], v90 offset:49152
	ds_read_b128 v[132:135], v90 offset:49184
	ds_read_b128 v[140:143], v90 offset:49216
	ds_read_b128 v[148:151], v90 offset:49248
	ds_read_b128 v[156:159], v90 offset:49280
	ds_read_b128 v[164:167], v90 offset:49312
	ds_read_b128 v[172:175], v90 offset:49344
	ds_read_b128 v[182:185], v90 offset:49376
	s_waitcnt lgkmcnt(7)
	v_mfma_f32_16x16x32_bf16 v[124:127], v[124:127], v[190:193], 0
	v_add_u32_e32 v56, 0, v110
	v_add_u32_e32 v59, 0x16500, v56
	ds_read_b32 v59, v59
	s_waitcnt lgkmcnt(7)
	v_mfma_f32_16x16x32_bf16 v[124:127], v[132:135], v[194:197], v[124:127]
	v_add_u32_e32 v56, 0x1a500, v56
	ds_read2_b32 v[128:129], v89 offset1:32
	ds_read_b32 v56, v56
	ds_read2_b32 v[130:131], v89 offset0:64 offset1:96
	s_waitcnt lgkmcnt(9)
	v_mfma_f32_16x16x32_bf16 v[124:127], v[140:143], v[198:201], v[124:127]
	s_waitcnt lgkmcnt(3)
	v_add_f32_e32 v59, v115, v59
	v_mul_f32_e32 v59, 0x3fb8aa3b, v59
	v_exp_f32_e32 v59, v59
	v_mfma_f32_16x16x32_bf16 v[124:127], v[148:151], v[202:205], v[124:127]
	s_waitcnt lgkmcnt(2)
	v_mov_b32_e32 v132, v128
	s_waitcnt lgkmcnt(0)
	v_mov_b32_e32 v133, v130
	v_mov_b32_e32 v130, v129
	v_mfma_f32_16x16x32_bf16 v[124:127], v[156:159], v[206:209], v[124:127]
	v_add_f32_e64 v128, v132, v130
	v_add_f32_e64 v129, v133, v131
	v_max_f32_e32 v56, v56, v56
	v_fmac_f32_e32 v128, v59, v129
	v_mfma_f32_16x16x32_bf16 v[124:127], v[164:167], v[210:213], v[124:127]
	v_max_f32_e64 v56, |v128|, v56
	v_rcp_f32_e32 v56, v56
	s_lshl_b32 s42, s53, 1
	v_mfma_f32_16x16x32_bf16 v[124:127], v[172:175], v[214:217], v[124:127]
	s_mov_b32 s59, s43
	s_add_i32 s16, s16, 4
	s_add_u32 s70, s70, 0x70000
	v_mfma_f32_16x16x32_bf16 v[124:127], v[182:185], v[218:221], v[124:127]
	s_addc_u32 s71, s71, 0
	v_add_u32_e32 v114, 0x80, v114
	v_add_u32_e32 v110, 0x80, v110
	v_mfma_f32_16x16x32_bf16 v[116:119], v[120:123], v[116:119], 0
	v_cvt_pk_bf16_f32 v120, v48, v49
	v_cvt_pk_bf16_f32 v121, v50, v51
	s_cmp_eq_u32 s70, 0x1b90000
	v_add_u32_e32 v111, 0x80, v111
	v_cvt_pk_bf16_f32 v122, v44, v45
	s_nop 5
	v_fma_f32 v76, v124, v59, v116
	v_fma_f32 v115, v125, v59, v117
	v_fma_f32 v116, v126, v59, v118
	v_fmac_f32_e32 v119, v127, v59
	v_mul_f32_e32 v76, v76, v56
	v_mul_f32_e32 v115, v115, v56
	v_mul_f32_e32 v117, v116, v56
	v_mul_f32_e32 v56, v119, v56
	v_mov_b64_e32 v[118:119], s[28:29]
	v_mad_i64_i32 v[118:119], s[72:73], v109, s84, v[118:119]
	v_lshl_add_u64 v[118:119], v[118:119], 0, s[42:43]
	v_lshl_add_u64 v[118:119], v[118:119], 0, s[58:59]
	v_lshl_add_u64 v[118:119], s[56:57], 1, v[118:119]
	v_lshl_add_u64 v[118:119], v[118:119], 0, v[60:61]
	v_add_co_u32_e32 v118, vcc, s85, v118
	v_cvt_pk_bf16_f32 v116, v76, v115
	v_cvt_pk_bf16_f32 v117, v117, v56
	v_add_u32_e32 v59, 0xc000, v113
	s_nop 0
	v_addc_co_u32_e32 v119, vcc, 0, v119, vcc
	global_store_dwordx2 v[118:119], v[116:117], off
	v_cvt_pk_bf16_f32 v116, v36, v37
	v_cvt_pk_bf16_f32 v117, v38, v39
	s_waitcnt lgkmcnt(0)
	s_barrier
	v_cvt_pk_bf16_f32 v126, v32, v33
	v_cvt_pk_bf16_f32 v127, v34, v35
	ds_write2_b64 v59, v[116:117], v[126:127] offset1:2
	v_cvt_pk_bf16_f32 v116, v28, v29
	v_cvt_pk_bf16_f32 v117, v30, v31
	v_add_u32_e32 v76, 0xe000, v113
	v_cvt_pk_bf16_f32 v118, v52, v53
	v_cvt_pk_bf16_f32 v119, v54, v55
	ds_write2_b64 v76, v[118:119], v[116:117] offset0:32 offset1:34
	v_cvt_pk_bf16_f32 v116, v24, v25
	v_cvt_pk_bf16_f32 v117, v26, v27
	ds_write2_b64 v85, v[120:121], v[116:117] offset1:2
	v_cvt_pk_bf16_f32 v116, v20, v21
	v_cvt_pk_bf16_f32 v117, v22, v23
	v_add_u32_e32 v115, 0xe000, v86
	v_add_u32_e32 v109, 32, v109
	v_cvt_pk_bf16_f32 v123, v46, v47
	v_cvt_pk_bf16_f32 v124, v40, v41
	v_cvt_pk_bf16_f32 v125, v42, v43
	ds_write2_b64 v115, v[122:123], v[116:117] offset0:32 offset1:34
	v_cvt_pk_bf16_f32 v116, v16, v17
	v_cvt_pk_bf16_f32 v117, v18, v19
	ds_write2_b64 v67, v[124:125], v[116:117] offset0:32 offset1:34
	s_cmp_eq_u32 s70, 0x1b90000
	s_cbranch_scc1 .LBB0_676
